# first grid barrier uses the same arrive/release/poll protocol as the other full barriers (census kept)
# baseline (speedup 1.0000x reference)
.LBB0_64:
	s_waitcnt lgkmcnt(0)
	v_mov_b32_e32 v0, 0x21020
	ds_read2_b32 v[2:3], v0 offset1:1
	s_lshl_b32 s16, s84, 8
	s_add_u32 s16, s76, s16
	s_addc_u32 s17, s77, 0
	v_mov_b32_e32 v1, 0x1000
	v_mov_b32_e32 v4, 1
	global_atomic_add v5, v1, v4, s[16:17] offset:1024 sc0
	buffer_inv sc1
	s_waitcnt vmcnt(0) lgkmcnt(0)
	v_readfirstlane_b32 s18, v5
	v_readfirstlane_b32 s19, v2
	v_readfirstlane_b32 s20, v3
	v_mov_b32_e32 v1, 0x3000
	s_add_u32 s18, s18, 1
	s_cmp_lg_u32 s18, s19
	s_cbranch_scc1 .Lxb_spin_0
	buffer_wbl2 sc1
	s_waitcnt vmcnt(0)
	global_atomic_add v1, v4, s[76:77] offset:1024
.Lxb_spin_0:
	global_load_dword v6, v1, s[76:77] offset:1024 sc1
	s_waitcnt vmcnt(0)
	v_readfirstlane_b32 s24, v6
	s_sub_u32 s24, s24, s20
	s_cmp_ge_i32 s24, 0
	s_cbranch_scc1 .LBB0_100
	s_sleep 1
	s_branch .Lxb_spin_0
